# v21 plus the next-tile DMA completion wait moved to right before the per-tile barrier (after the hoisted flag/address work) in MLA, MOBA, SLC
# baseline (speedup 1.0000x reference)
; #define FA_SBAR() __builtin_amdgcn_sched_barrier(0)
; #define FA_WRITET(bf) do { *(LAS half8*)(lds + OFF_K + (bf) * SHM_K + kws) = st_k0; *(LAS half8*)(lds + OFF_K + (bf) * SHM_K + kws + 32 * 256) = st_k1; \
;         *(LAS half8*)(lds + OFF_V + (bf) * SHM_V + vst0) = st_v0; *(LAS half8*)(lds + OFF_V + (bf) * SHM_V + vst1) = st_v1; \
;         if constexpr (MLA) *(LAS half8*)(lds + OFF_KR + (bf) * SHM_KR + krw) = st_kr; } while (0)
; template <int KIND>
; __device__ __forceinline__ void run_unit(LAS char* lds, const UnitArgs& U, int tid_in) {
;     ...
;     for (int t = 0; t < NT; ++t) {
;         if (t + 1 < NT) FA_LOADT(U.j_lo + t + 1);
;         FA_SBAR();
;         FA_STEP(t);
;         FA_SBAR();
;         if (t + 1 < NT) { asm volatile("s_waitcnt vmcnt(0)" ::: "memory"); FA_WRITET((t + 1) & 1); dm_lo = dn_lo; dm_hi = dn_hi; }
;         __syncthreads();
.Lmoba_rot:
	s_cmp_lt_u32 s23, s15
	s_cselect_b64 s[6:7], -1, 0
	s_sub_i32 s8, s22, 63
	s_and_b32 s9, s23, 1
	v_mov_b32_e32 v2, s9
	s_cmp_gt_i32 s8, s24
	s_cselect_b64 vcc, -1, 0
	v_lshlrev_b32_e32 v2, 14, v2
	v_add_u32_e32 v4, v229, v2
	v_add_u32_e32 v16, v4, v230
	v_add_u32_e32 v17, v4, v231
	v_add_u32_e32 v102, v4, v232
	v_add_u32_e32 v103, v4, v233
	s_cmp_eq_u32 s13, s23
	s_waitcnt vmcnt(0) lgkmcnt(0)
	s_barrier
	s_cbranch_scc1 .LBB0_4964
	s_cbranch_vccnz .Lmoba_skipq
	ds_read_b128 v[4:7], v16 offset:32768
	ds_read_b128 v[8:11], v16 offset:40960
	ds_read_b128 v[12:15], v17 offset:32768
	ds_read_b128 v[82:85], v17 offset:40960
	ds_read_b128 v[86:89], v102 offset:32768
	ds_read_b128 v[90:93], v102 offset:40960
	ds_read_b128 v[94:97], v103 offset:32768
	ds_read_b128 v[98:101], v103 offset:40960
	s_and_b64 vcc, exec, s[6:7]
	s_cbranch_vccz .Lmoba_q_nold
	v_readfirstlane_b32 vcc_hi, v0
	s_and_b32 vcc_lo, s37, 0x4000
	s_lshr_b32 vcc_hi, vcc_hi, 6
	s_lshl_b32 vcc_hi, vcc_hi, 10
	s_add_i32 vcc_lo, vcc_lo, vcc_hi
	v_add_u32_e32 v114, s22, v204
	v_add_u32_e32 v116, 1, v114
	v_ashrrev_i32_e32 v117, 31, v116
	v_add_u32_e32 v120, 33, v114
	v_lshlrev_b64 v[116:117], 8, v[116:117]
	v_ashrrev_i32_e32 v121, 31, v120
	s_add_i32 m0, vcc_lo, 0x8000
	v_lshl_add_u64 v[118:119], v[206:207], 0, v[116:117]
	v_lshlrev_b64 v[120:121], 8, v[120:121]
	global_load_lds_dwordx4 v[118:119], off
	s_add_i32 m0, vcc_lo, 0xa000
	v_lshl_add_u64 v[122:123], v[206:207], 0, v[120:121]
	v_lshl_add_u64 v[116:117], v[208:209], 0, v[116:117]
	global_load_lds_dwordx4 v[122:123], off
	s_mov_b32 m0, vcc_lo
	v_lshl_add_u64 v[118:119], v[208:209], 0, v[120:121]
	s_nop 0
	global_load_lds_dwordx4 v[116:117], off
	s_add_i32 m0, vcc_lo, 0x2000
	s_nop 0
	global_load_lds_dwordx4 v[118:119], off

; #define FA_SBAR() __builtin_amdgcn_sched_barrier(0)
; #define FA_RD8(S, d0) do { constexpr int b_ = v_rd_off(d0, 0, 0); FA_TRRD(S##l0, b_); FA_TRRD(S##h0, b_ + 2048); FA_TRRD(S##l1, b_ + 4096); FA_TRRD(S##h1, b_ + 6144); FA_TRRD(S##l2, b_ + 8192); FA_TRRD(S##h2, b_ + 10240); FA_TRRD(S##l3, b_ + 12288); FA_TRRD(S##h3, b_ + 14336); } while (0)
; __device__ __forceinline__ void partialSM(f32x16& p0, f32x16& p1, float& m_reg, float& mn, float& alpha, const float sc, const float C2) {
;     ...
;     const float mnL = -mn * C2;
; #pragma unroll
;     for (int r = 0; r < 16; ++r) p0[r] = __builtin_amdgcn_exp2f(fmaf(p0[r], C2, mnL));
; #pragma unroll
;     for (int r = 0; r < 16; ++r) p1[r] = __builtin_amdgcn_exp2f(fmaf(p1[r], C2, mnL));
; }
; __device__ __forceinline__ void finishSM(const f32x16& p0, const f32x16& p1, float alpha, float& l_reg, half8& pa0, half8& pa1, half8& pa2, half8& pa3) {
;     f32x2 s2 = {0.f, 0.f};
; #pragma unroll
;     for (int r = 0; r < 16; r += 2) { s2 += (f32x2){p0[r], p0[r + 1]}; s2 += (f32x2){p1[r], p1[r + 1]}; }
;     float ps = s2[0] + s2[1];
;     { auto rr = __builtin_amdgcn_permlane32_swap(__float_as_uint(ps), __float_as_uint(ps), false, false);
;       ps = __uint_as_float(rr[0]) + __uint_as_float(rr[1]); }
;     l_reg = l_reg * alpha + ps;
;     ...
;     FA_PK4(p0, 0, pa0); FA_PK4(p0, 8, pa1); FA_PK4(p1, 0, pa2); FA_PK4(p1, 8, pa3);
; __device__ __forceinline__ void pv_tile2(f32x16* o, int vb0, half8 pa0, half8 pa1, half8 pa2, half8 pa3) {
;     ...
;     s16x4 al0, al1, al2, al3, ah0, ah1, ah2, ah3, bl0, bl1, bl2, bl3, bh0, bh1, bh2, bh3;
;     FA_RD8(a, 0);
;     FA_RD8(b, 1); asm volatile("s_waitcnt lgkmcnt(8)" ::: "memory"); FA_SBAR(); FA_MM4(a, 0); FA_SBAR();
;     FA_RD8(a, 2); asm volatile("s_waitcnt lgkmcnt(8)" ::: "memory"); FA_SBAR(); FA_MM4(b, 1); FA_SBAR();
;     FA_RD8(b, 3); asm volatile("s_waitcnt lgkmcnt(8)" ::: "memory"); FA_SBAR(); FA_MM4(a, 2); FA_SBAR();
;     asm volatile("s_waitcnt lgkmcnt(0)" ::: "memory"); FA_SBAR(); FA_MM4(b, 3);
.Lmoba_fast:
.LBB0_4961:
	v_mul_f32_e32 v5, 0xbe0293ee, v236
	v_fmamk_f32 v6, v98, 0x3e0293ee, v5
	v_fmamk_f32 v7, v99, 0x3e0293ee, v5
	v_exp_f32_e32 v6, v6
	v_exp_f32_e32 v7, v7
	v_fmamk_f32 v82, v82, 0x3e0293ee, v5
	v_fmamk_f32 v83, v83, 0x3e0293ee, v5
	v_fmamk_f32 v8, v100, 0x3e0293ee, v5
	v_fmamk_f32 v9, v101, 0x3e0293ee, v5
	v_exp_f32_e32 v82, v82
	v_exp_f32_e32 v83, v83
	v_exp_f32_e32 v8, v8
	v_exp_f32_e32 v9, v9
	v_fmamk_f32 v84, v84, 0x3e0293ee, v5
	v_fmamk_f32 v85, v85, 0x3e0293ee, v5
	v_fmamk_f32 v10, v102, 0x3e0293ee, v5
	v_fmamk_f32 v11, v103, 0x3e0293ee, v5
	v_exp_f32_e32 v84, v84
	v_exp_f32_e32 v85, v85
	v_exp_f32_e32 v10, v10
	v_exp_f32_e32 v11, v11
	v_fmamk_f32 v86, v86, 0x3e0293ee, v5
	v_fmamk_f32 v87, v87, 0x3e0293ee, v5
	v_pk_add_f32 v[102:103], v[6:7], 0 op_sel_hi:[1,0]
	v_fmamk_f32 v12, v104, 0x3e0293ee, v5
	v_fmamk_f32 v13, v105, 0x3e0293ee, v5
	v_exp_f32_e32 v86, v86
	v_exp_f32_e32 v87, v87
	v_pk_add_f32 v[102:103], v[82:83], v[102:103]
	v_exp_f32_e32 v12, v12
	v_exp_f32_e32 v13, v13
	v_fmamk_f32 v88, v88, 0x3e0293ee, v5
	v_fmamk_f32 v89, v89, 0x3e0293ee, v5
	v_pk_add_f32 v[102:103], v[8:9], v[102:103]
	v_fmamk_f32 v14, v106, 0x3e0293ee, v5
	v_fmamk_f32 v15, v107, 0x3e0293ee, v5
	v_exp_f32_e32 v88, v88
	v_exp_f32_e32 v89, v89
	v_pk_add_f32 v[102:103], v[84:85], v[102:103]
	v_exp_f32_e32 v14, v14
	v_exp_f32_e32 v15, v15
	v_fmamk_f32 v90, v90, 0x3e0293ee, v5
	v_fmamk_f32 v91, v91, 0x3e0293ee, v5
	v_pk_add_f32 v[102:103], v[10:11], v[102:103]
	v_fmamk_f32 v16, v108, 0x3e0293ee, v5
	v_fmamk_f32 v17, v109, 0x3e0293ee, v5
	v_exp_f32_e32 v90, v90
	v_exp_f32_e32 v91, v91
	v_pk_add_f32 v[102:103], v[86:87], v[102:103]
	v_exp_f32_e32 v16, v16
	v_exp_f32_e32 v17, v17
	v_fmamk_f32 v92, v92, 0x3e0293ee, v5
	v_fmamk_f32 v93, v93, 0x3e0293ee, v5
	v_pk_add_f32 v[102:103], v[12:13], v[102:103]
	v_fmamk_f32 v98, v110, 0x3e0293ee, v5
	v_fmamk_f32 v99, v111, 0x3e0293ee, v5
	v_exp_f32_e32 v92, v92
	v_exp_f32_e32 v93, v93
	v_pk_add_f32 v[102:103], v[88:89], v[102:103]
	v_exp_f32_e32 v98, v98
	v_exp_f32_e32 v99, v99
	v_fmamk_f32 v94, v94, 0x3e0293ee, v5
	v_fmamk_f32 v95, v95, 0x3e0293ee, v5
	v_pk_add_f32 v[102:103], v[14:15], v[102:103]
	v_fmamk_f32 v100, v112, 0x3e0293ee, v5
	v_fmamk_f32 v101, v113, 0x3e0293ee, v5
	v_exp_f32_e32 v94, v94
	v_exp_f32_e32 v95, v95
	v_pk_add_f32 v[102:103], v[90:91], v[102:103]
	v_exp_f32_e32 v100, v100
	v_exp_f32_e32 v101, v101
	v_fmamk_f32 v96, v96, 0x3e0293ee, v5
	v_fmac_f32_e32 v5, 0x3e0293ee, v97
	v_pk_add_f32 v[102:103], v[16:17], v[102:103]
	v_exp_f32_e32 v96, v96
	v_exp_f32_e32 v97, v5
	v_pk_add_f32 v[102:103], v[92:93], v[102:103]
	v_cvt_pk_f16_f32 v4, v6, v7
	v_pk_add_f32 v[102:103], v[98:99], v[102:103]
	v_cvt_pk_f16_f32 v5, v8, v9
	v_pk_add_f32 v[102:103], v[94:95], v[102:103]
	v_cvt_pk_f16_f32 v6, v10, v11
	v_pk_add_f32 v[102:103], v[100:101], v[102:103]
	v_cvt_pk_f16_f32 v7, v12, v13
	v_pk_add_f32 v[102:103], v[96:97], v[102:103]
	v_cvt_pk_f16_f32 v8, v14, v15
	v_pk_add_f32 v[102:103], v[102:103], v[102:103] op_sel:[0,1] op_sel_hi:[1,0]
	v_cvt_pk_f16_f32 v9, v16, v17
	v_mov_b32_e32 v103, v102
	v_cvt_pk_f16_f32 v10, v98, v99
	v_cvt_pk_f16_f32 v11, v100, v101
	v_permlane32_swap_b32_e32 v102, v103
	v_cvt_pk_f16_f32 v12, v82, v83
	v_add_f32_e32 v103, v102, v103
	v_cvt_pk_f16_f32 v13, v84, v85
	v_fma_f32 v237, v237, v118, v103
	v_cvt_pk_f16_f32 v14, v86, v87
	v_cvt_pk_f16_f32 v15, v88, v89
	v_cvt_pk_f16_f32 v82, v90, v91
	v_cvt_pk_f16_f32 v83, v92, v93
	v_cvt_pk_f16_f32 v84, v94, v95
	v_cvt_pk_f16_f32 v85, v96, v97
	v_permlane32_swap_b32_e32 v4, v6
	v_permlane32_swap_b32_e32 v5, v7
	v_permlane32_swap_b32_e32 v8, v10
	v_permlane32_swap_b32_e32 v9, v11
	v_permlane32_swap_b32_e32 v12, v14
	v_permlane32_swap_b32_e32 v13, v15
	v_permlane32_swap_b32_e32 v82, v84
	v_permlane32_swap_b32_e32 v83, v85
	v_add_u32_e32 v2, v234, v2
	ds_read_b64_tr_b16 v[86:87], v2 offset:0
	ds_read_b64_tr_b16 v[88:89], v2 offset:0x800
	ds_read_b64_tr_b16 v[90:91], v2 offset:0x1000
	ds_read_b64_tr_b16 v[92:93], v2 offset:0x1800
	ds_read_b64_tr_b16 v[94:95], v2 offset:0x2000
	ds_read_b64_tr_b16 v[96:97], v2 offset:0x2800
	ds_read_b64_tr_b16 v[98:99], v2 offset:0x3000
	ds_read_b64_tr_b16 v[100:101], v2 offset:0x3800
	ds_read_b64_tr_b16 v[102:103], v2 offset:0x200
	ds_read_b64_tr_b16 v[104:105], v2 offset:0xa00
	ds_read_b64_tr_b16 v[106:107], v2 offset:0x1200
	ds_read_b64_tr_b16 v[108:109], v2 offset:0x1a00
	ds_read_b64_tr_b16 v[110:111], v2 offset:0x2200
	ds_read_b64_tr_b16 v[112:113], v2 offset:0x2a00
	ds_read_b64_tr_b16 v[114:115], v2 offset:0x3200
	ds_read_b64_tr_b16 v[116:117], v2 offset:0x3a00
	s_waitcnt lgkmcnt(8)
	s_nop 0
	v_mfma_f32_32x32x16_f16 v[66:81], v[4:7], v[86:89], v[66:81]
	v_mfma_f32_32x32x16_f16 v[66:81], v[8:11], v[90:93], v[66:81]
	v_mfma_f32_32x32x16_f16 v[66:81], v[12:15], v[94:97], v[66:81]
	v_mfma_f32_32x32x16_f16 v[66:81], v[82:85], v[98:101], v[66:81]
	ds_read_b64_tr_b16 v[86:87], v2 offset:0x400
	ds_read_b64_tr_b16 v[88:89], v2 offset:0xc00
	ds_read_b64_tr_b16 v[90:91], v2 offset:0x1400
	ds_read_b64_tr_b16 v[92:93], v2 offset:0x1c00
	ds_read_b64_tr_b16 v[94:95], v2 offset:0x2400
	ds_read_b64_tr_b16 v[96:97], v2 offset:0x2c00
	ds_read_b64_tr_b16 v[98:99], v2 offset:0x3400
	ds_read_b64_tr_b16 v[100:101], v2 offset:0x3c00
	s_waitcnt lgkmcnt(8)
	v_mfma_f32_32x32x16_f16 v[50:65], v[4:7], v[102:105], v[50:65]
	v_mfma_f32_32x32x16_f16 v[50:65], v[8:11], v[106:109], v[50:65]
	v_mfma_f32_32x32x16_f16 v[50:65], v[12:15], v[110:113], v[50:65]
	v_mfma_f32_32x32x16_f16 v[50:65], v[82:85], v[114:117], v[50:65]
	ds_read_b64_tr_b16 v[102:103], v2 offset:0x600
	ds_read_b64_tr_b16 v[104:105], v2 offset:0xe00
	ds_read_b64_tr_b16 v[106:107], v2 offset:0x1600
	ds_read_b64_tr_b16 v[108:109], v2 offset:0x1e00
	ds_read_b64_tr_b16 v[110:111], v2 offset:0x2600
	ds_read_b64_tr_b16 v[112:113], v2 offset:0x2e00
	ds_read_b64_tr_b16 v[114:115], v2 offset:0x3600
	ds_read_b64_tr_b16 v[116:117], v2 offset:0x3e00
	s_waitcnt lgkmcnt(8)
	v_mfma_f32_32x32x16_f16 v[34:49], v[4:7], v[86:89], v[34:49]
	v_mfma_f32_32x32x16_f16 v[34:49], v[8:11], v[90:93], v[34:49]
	v_mfma_f32_32x32x16_f16 v[34:49], v[12:15], v[94:97], v[34:49]
	v_mfma_f32_32x32x16_f16 v[34:49], v[82:85], v[98:101], v[34:49]
	s_waitcnt lgkmcnt(0)
	v_mfma_f32_32x32x16_f16 v[18:33], v[4:7], v[102:105], v[18:33]
	v_mfma_f32_32x32x16_f16 v[18:33], v[8:11], v[106:109], v[18:33]
	v_mfma_f32_32x32x16_f16 v[18:33], v[12:15], v[110:113], v[18:33]
	v_mfma_f32_32x32x16_f16 v[18:33], v[82:85], v[114:117], v[18:33]
; #define FA_SBAR() __builtin_amdgcn_sched_barrier(0)
; #define FA_WRITET(bf) do { *(LAS half8*)(lds + OFF_K + (bf) * SHM_K + kws) = st_k0; *(LAS half8*)(lds + OFF_K + (bf) * SHM_K + kws + 32 * 256) = st_k1; \
;         *(LAS half8*)(lds + OFF_V + (bf) * SHM_V + vst0) = st_v0; *(LAS half8*)(lds + OFF_V + (bf) * SHM_V + vst1) = st_v1; \
;         if constexpr (MLA) *(LAS half8*)(lds + OFF_KR + (bf) * SHM_KR + krw) = st_kr; } while (0)
; template <int KIND>
; __device__ __forceinline__ void run_unit(LAS char* lds, const UnitArgs& U, int tid_in) {
;     ...
;     for (int t = 0; t < NT; ++t) {
;         if (t + 1 < NT) FA_LOADT(U.j_lo + t + 1);
;         FA_SBAR();
;         FA_STEP(t);
;         FA_SBAR();
;         if (t + 1 < NT) { asm volatile("s_waitcnt vmcnt(0)" ::: "memory"); FA_WRITET((t + 1) & 1); dm_lo = dn_lo; dm_hi = dn_hi; }
;         __syncthreads();
.LBB0_4962:
	s_branch .LBB0_4947
.Lmoba_skipq:
	s_and_b64 vcc, exec, s[6:7]
	s_cbranch_vccz .LBB0_4962
	v_readfirstlane_b32 vcc_hi, v0
	s_and_b32 vcc_lo, s37, 0x4000
	s_lshr_b32 vcc_hi, vcc_hi, 6
	s_lshl_b32 vcc_hi, vcc_hi, 10
	s_add_i32 vcc_lo, vcc_lo, vcc_hi
	v_add_u32_e32 v2, s22, v204
	v_add_u32_e32 v4, 1, v2
	v_ashrrev_i32_e32 v5, 31, v4
	v_add_u32_e32 v8, 33, v2
	v_lshlrev_b64 v[4:5], 8, v[4:5]
	v_ashrrev_i32_e32 v9, 31, v8
	s_add_i32 m0, vcc_lo, 0x8000
	v_lshl_add_u64 v[6:7], v[206:207], 0, v[4:5]
	v_lshlrev_b64 v[8:9], 8, v[8:9]
	global_load_lds_dwordx4 v[6:7], off
	s_add_i32 m0, vcc_lo, 0xa000
	v_lshl_add_u64 v[10:11], v[206:207], 0, v[8:9]
	v_lshl_add_u64 v[4:5], v[208:209], 0, v[4:5]
	global_load_lds_dwordx4 v[10:11], off
	s_mov_b32 m0, vcc_lo
	v_lshl_add_u64 v[6:7], v[208:209], 0, v[8:9]
	s_nop 0
	global_load_lds_dwordx4 v[4:5], off
	s_add_i32 m0, vcc_lo, 0x2000
	s_nop 0
	global_load_lds_dwordx4 v[6:7], off
	s_branch .LBB0_4962

; #define FA_SBAR() __builtin_amdgcn_sched_barrier(0)
; #define FA_WRITET(bf) do { *(LAS half8*)(lds + OFF_K + (bf) * SHM_K + kws) = st_k0; *(LAS half8*)(lds + OFF_K + (bf) * SHM_K + kws + 32 * 256) = st_k1; \
;         *(LAS half8*)(lds + OFF_V + (bf) * SHM_V + vst0) = st_v0; *(LAS half8*)(lds + OFF_V + (bf) * SHM_V + vst1) = st_v1; \
;         if constexpr (MLA) *(LAS half8*)(lds + OFF_KR + (bf) * SHM_KR + krw) = st_kr; } while (0)
; template <int KIND>
; __device__ __forceinline__ void run_unit(LAS char* lds, const UnitArgs& U, int tid_in) {
;     ...
;     for (int t = 0; t < NT; ++t) {
;         if (t + 1 < NT) FA_LOADT(U.j_lo + t + 1);
;         FA_SBAR();
;         FA_STEP(t);
;         FA_SBAR();
;         if (t + 1 < NT) { asm volatile("s_waitcnt vmcnt(0)" ::: "memory"); FA_WRITET((t + 1) & 1); dm_lo = dn_lo; dm_hi = dn_hi; }
;         __syncthreads();
.Lmla_rot:
	s_cmp_lt_u32 s23, s15
	s_cselect_b64 s[6:7], -1, 0
	s_and_b32 s8, s23, 1
	v_mov_b32_e32 v4, s8
	s_cmp_gt_i32 s22, s17
	s_cselect_b64 vcc, -1, 0
	v_lshlrev_b32_e32 v2, 14, v4
	v_add_u32_e32 v5, v209, v2
	v_add_u32_e32 v214, v5, v220
	v_add_u32_e32 v248, v5, v221
	v_add_u32_e32 v249, v5, v222
	v_add_u32_e32 v5, v5, v223
	s_cmp_eq_u32 s13, s23
	s_waitcnt vmcnt(0) lgkmcnt(0)
	s_barrier
	s_cbranch_scc1 .LBB0_4984
	s_cbranch_vccnz .Lmla_skipq
	ds_read_b128 v[6:9], v214 offset:32768
	ds_read_b128 v[10:13], v214 offset:40960
	ds_read_b128 v[14:17], v248 offset:32768
	ds_read_b128 v[230:233], v248 offset:40960
	ds_read_b128 v[234:237], v249 offset:32768
	ds_read_b128 v[240:243], v249 offset:40960
	ds_read_b128 v[244:247], v5 offset:32768
	ds_read_b128 v[194:197], v5 offset:40960
	s_and_b64 vcc, exec, s[6:7]
	s_cbranch_vccz .Lmla_q_nold
	v_readfirstlane_b32 s9, v0
	s_add_i32 s8, s23, 1
	s_and_b32 s8, s8, 1
	s_lshr_b32 s9, s9, 6
	s_lshl_b32 s9, s9, 10
	s_lshl_b32 vcc_lo, s8, 14
	s_add_i32 vcc_lo, vcc_lo, s9
	s_lshl_b32 s8, s8, 13
	s_add_i32 s8, s8, s9
	s_add_i32 s8, s8, 0x10000
	v_add_u32_e32 v98, s22, v182
	v_add_u32_e32 v100, 64, v98
	v_ashrrev_i32_e32 v101, 31, v100
	v_add_u32_e32 v104, 0x60, v98
	v_lshlrev_b64 v[100:101], 8, v[100:101]
	v_ashrrev_i32_e32 v105, 31, v104
	s_add_i32 m0, vcc_lo, 0x8000
	v_lshl_add_u64 v[102:103], v[184:185], 0, v[100:101]
	v_lshlrev_b64 v[104:105], 8, v[104:105]
	global_load_lds_dwordx4 v[102:103], off
	s_add_i32 m0, vcc_lo, 0xa000
	v_lshl_add_u64 v[106:107], v[184:185], 0, v[104:105]
	v_lshl_add_u64 v[100:101], v[186:187], 0, v[100:101]
	global_load_lds_dwordx4 v[106:107], off
	s_mov_b32 m0, vcc_lo
	v_lshl_add_u64 v[102:103], v[186:187], 0, v[104:105]
	v_add_u32_e32 v104, s22, v227
	global_load_lds_dwordx4 v[100:101], off
	s_add_i32 m0, vcc_lo, 0x2000
	v_ashrrev_i32_e32 v105, 31, v104
	v_lshlrev_b64 v[104:105], 7, v[104:105]
	global_load_lds_dwordx4 v[102:103], off
	s_mov_b32 m0, s8
	v_lshl_add_u64 v[104:105], v[188:189], 0, v[104:105]
	global_load_lds_dwordx4 v[104:105], off

; #define FA_SBAR() __builtin_amdgcn_sched_barrier(0)
; #define FA_WRITET(bf) do { *(LAS half8*)(lds + OFF_K + (bf) * SHM_K + kws) = st_k0; *(LAS half8*)(lds + OFF_K + (bf) * SHM_K + kws + 32 * 256) = st_k1; \
;         *(LAS half8*)(lds + OFF_V + (bf) * SHM_V + vst0) = st_v0; *(LAS half8*)(lds + OFF_V + (bf) * SHM_V + vst1) = st_v1; \
;         if constexpr (MLA) *(LAS half8*)(lds + OFF_KR + (bf) * SHM_KR + krw) = st_kr; } while (0)
; template <int KIND>
; __device__ __forceinline__ void run_unit(LAS char* lds, const UnitArgs& U, int tid_in) {
;     ...
;     for (int t = 0; t < NT; ++t) {
;         if (t + 1 < NT) FA_LOADT(U.j_lo + t + 1);
;         FA_SBAR();
;         FA_STEP(t);
;         FA_SBAR();
;         if (t + 1 < NT) { asm volatile("s_waitcnt vmcnt(0)" ::: "memory"); FA_WRITET((t + 1) & 1); dm_lo = dn_lo; dm_hi = dn_hi; }
;         __syncthreads();
.LBB0_4982:
	s_add_i32 s23, s23, 1
	s_branch .LBB0_4971

; #define FA_SBAR() __builtin_amdgcn_sched_barrier(0)
; #define FA_WRITET(bf) do { *(LAS half8*)(lds + OFF_K + (bf) * SHM_K + kws) = st_k0; *(LAS half8*)(lds + OFF_K + (bf) * SHM_K + kws + 32 * 256) = st_k1; \
;         *(LAS half8*)(lds + OFF_V + (bf) * SHM_V + vst0) = st_v0; *(LAS half8*)(lds + OFF_V + (bf) * SHM_V + vst1) = st_v1; \
;         if constexpr (MLA) *(LAS half8*)(lds + OFF_KR + (bf) * SHM_KR + krw) = st_kr; } while (0)
; template <int KIND>
; __device__ __forceinline__ void run_unit(LAS char* lds, const UnitArgs& U, int tid_in) {
;     ...
;     for (int t = 0; t < NT; ++t) {
;         if (t + 1 < NT) FA_LOADT(U.j_lo + t + 1);
;         FA_SBAR();
;         FA_STEP(t);
;         FA_SBAR();
;         if (t + 1 < NT) { asm volatile("s_waitcnt vmcnt(0)" ::: "memory"); FA_WRITET((t + 1) & 1); dm_lo = dn_lo; dm_hi = dn_hi; }
;         __syncthreads();
.Lslc_rot:
	s_cmp_lt_u32 s25, s15
	s_cselect_b64 s[6:7], -1, 0
	s_sub_i32 s10, s22, 63
	s_and_b32 s11, s25, 1
	v_mov_b32_e32 v2, s11
	s_cmp_gt_i32 s10, s24
	s_cselect_b64 vcc, -1, 0
	v_lshlrev_b32_e32 v2, 14, v2
	v_add_u32_e32 v4, v182, v2
	v_add_u32_e32 v16, v4, v183
	v_add_u32_e32 v17, v4, v184
	v_add_u32_e32 v191, v4, v185
	v_add_u32_e32 v196, v4, v186
	s_cmp_eq_u32 s13, s25
	s_waitcnt vmcnt(0) lgkmcnt(0)
	s_barrier
	s_cbranch_scc1 .LBB0_5002
	s_cbranch_vccnz .Lslc_skipq
	ds_read_b128 v[4:7], v16 offset:32768
	ds_read_b128 v[8:11], v16 offset:40960
	ds_read_b128 v[12:15], v17 offset:32768
	ds_read_b128 v[192:195], v17 offset:40960
	ds_read_b128 v[204:207], v191 offset:32768
	ds_read_b128 v[220:223], v191 offset:40960
	ds_read_b128 v[224:227], v196 offset:32768
	ds_read_b128 v[228:231], v196 offset:40960
	s_and_b64 vcc, exec, s[6:7]
	s_cbranch_vccz .Lslc_q_nold
	v_readfirstlane_b32 vcc_hi, v0
	s_and_b32 vcc_lo, s37, 0x4000
	s_lshr_b32 vcc_hi, vcc_hi, 6
	s_lshl_b32 vcc_hi, vcc_hi, 10
	s_add_i32 vcc_lo, vcc_lo, vcc_hi
	v_add_u32_e32 v98, s22, v166
	v_add_u32_e32 v100, 1, v98
	v_ashrrev_i32_e32 v101, 31, v100
	v_add_u32_e32 v104, 33, v98
	v_lshlrev_b64 v[100:101], 8, v[100:101]
	v_ashrrev_i32_e32 v105, 31, v104
	s_add_i32 m0, vcc_lo, 0x8000
	v_lshl_add_u64 v[102:103], v[170:171], 0, v[100:101]
	v_lshlrev_b64 v[104:105], 8, v[104:105]
	global_load_lds_dwordx4 v[102:103], off
	s_add_i32 m0, vcc_lo, 0xa000
	v_lshl_add_u64 v[106:107], v[170:171], 0, v[104:105]
	v_lshl_add_u64 v[100:101], v[172:173], 0, v[100:101]
	global_load_lds_dwordx4 v[106:107], off
	s_mov_b32 m0, vcc_lo
	v_lshl_add_u64 v[102:103], v[172:173], 0, v[104:105]
	s_nop 0
	global_load_lds_dwordx4 v[100:101], off
	s_add_i32 m0, vcc_lo, 0x2000
	s_nop 0
	global_load_lds_dwordx4 v[102:103], off

; #define FA_SBAR() __builtin_amdgcn_sched_barrier(0)
; #define FA_RD8(S, d0) do { constexpr int b_ = v_rd_off(d0, 0, 0); FA_TRRD(S##l0, b_); FA_TRRD(S##h0, b_ + 2048); FA_TRRD(S##l1, b_ + 4096); FA_TRRD(S##h1, b_ + 6144); FA_TRRD(S##l2, b_ + 8192); FA_TRRD(S##h2, b_ + 10240); FA_TRRD(S##l3, b_ + 12288); FA_TRRD(S##h3, b_ + 14336); } while (0)
; __device__ __forceinline__ void partialSM(f32x16& p0, f32x16& p1, float& m_reg, float& mn, float& alpha, const float sc, const float C2) {
;     ...
;     const float mnL = -mn * C2;
; #pragma unroll
;     for (int r = 0; r < 16; ++r) p0[r] = __builtin_amdgcn_exp2f(fmaf(p0[r], C2, mnL));
; #pragma unroll
;     for (int r = 0; r < 16; ++r) p1[r] = __builtin_amdgcn_exp2f(fmaf(p1[r], C2, mnL));
; }
; __device__ __forceinline__ void finishSM(const f32x16& p0, const f32x16& p1, float alpha, float& l_reg, half8& pa0, half8& pa1, half8& pa2, half8& pa3) {
;     f32x2 s2 = {0.f, 0.f};
; #pragma unroll
;     for (int r = 0; r < 16; r += 2) { s2 += (f32x2){p0[r], p0[r + 1]}; s2 += (f32x2){p1[r], p1[r + 1]}; }
;     float ps = s2[0] + s2[1];
;     { auto rr = __builtin_amdgcn_permlane32_swap(__float_as_uint(ps), __float_as_uint(ps), false, false);
;       ps = __uint_as_float(rr[0]) + __uint_as_float(rr[1]); }
;     l_reg = l_reg * alpha + ps;
;     ...
;     FA_PK4(p0, 0, pa0); FA_PK4(p0, 8, pa1); FA_PK4(p1, 0, pa2); FA_PK4(p1, 8, pa3);
; __device__ __forceinline__ void pv_tile2(f32x16* o, int vb0, half8 pa0, half8 pa1, half8 pa2, half8 pa3) {
;     ...
;     s16x4 al0, al1, al2, al3, ah0, ah1, ah2, ah3, bl0, bl1, bl2, bl3, bh0, bh1, bh2, bh3;
;     FA_RD8(a, 0);
;     FA_RD8(b, 1); asm volatile("s_waitcnt lgkmcnt(8)" ::: "memory"); FA_SBAR(); FA_MM4(a, 0); FA_SBAR();
;     FA_RD8(a, 2); asm volatile("s_waitcnt lgkmcnt(8)" ::: "memory"); FA_SBAR(); FA_MM4(b, 1); FA_SBAR();
;     FA_RD8(b, 3); asm volatile("s_waitcnt lgkmcnt(8)" ::: "memory"); FA_SBAR(); FA_MM4(a, 2); FA_SBAR();
;     asm volatile("s_waitcnt lgkmcnt(0)" ::: "memory"); FA_SBAR(); FA_MM4(b, 3);
.Lslc_fast:
.LBB0_4999:
	v_mul_f32_e32 v111, 0xbe0293ee, v189
	v_fmamk_f32 v92, v193, 0x3e0293ee, v111
	v_fmamk_f32 v93, v204, 0x3e0293ee, v111
	v_exp_f32_e32 v92, v92
	v_exp_f32_e32 v93, v93
	v_fmamk_f32 v82, v82, 0x3e0293ee, v111
	v_fmamk_f32 v83, v83, 0x3e0293ee, v111
	v_fmamk_f32 v94, v191, 0x3e0293ee, v111
	v_fmamk_f32 v95, v192, 0x3e0293ee, v111
	v_exp_f32_e32 v82, v82
	v_exp_f32_e32 v83, v83
	v_exp_f32_e32 v94, v94
	v_exp_f32_e32 v95, v95
	v_fmamk_f32 v16, v16, 0x3e0293ee, v111
	v_fmamk_f32 v17, v17, 0x3e0293ee, v111
	v_fmamk_f32 v96, v101, 0x3e0293ee, v111
	v_fmamk_f32 v97, v102, 0x3e0293ee, v111
	v_fmamk_f32 v99, v99, 0x3e0293ee, v111
	v_exp_f32_e32 v16, v16
	v_exp_f32_e32 v17, v17
	v_fmamk_f32 v12, v12, 0x3e0293ee, v111
	v_fmamk_f32 v10, v10, 0x3e0293ee, v111
	v_fmamk_f32 v8, v8, 0x3e0293ee, v111
	v_fmamk_f32 v6, v6, 0x3e0293ee, v111
	v_fmamk_f32 v4, v4, 0x3e0293ee, v111
	v_exp_f32_e32 v96, v96
	v_exp_f32_e32 v97, v97
	v_exp_f32_e32 v102, v99
	v_fmamk_f32 v99, v100, 0x3e0293ee, v111
	v_fmamk_f32 v98, v98, 0x3e0293ee, v111
	v_fmamk_f32 v90, v90, 0x3e0293ee, v111
	v_fmamk_f32 v88, v88, 0x3e0293ee, v111
	v_fmamk_f32 v89, v89, 0x3e0293ee, v111
	v_fmamk_f32 v86, v86, 0x3e0293ee, v111
	v_fmamk_f32 v87, v87, 0x3e0293ee, v111
	v_fmamk_f32 v84, v84, 0x3e0293ee, v111
	v_fmamk_f32 v85, v85, 0x3e0293ee, v111
	v_fmamk_f32 v14, v14, 0x3e0293ee, v111
	v_fmamk_f32 v15, v15, 0x3e0293ee, v111
	v_exp_f32_e32 v100, v12
	v_fmamk_f32 v12, v13, 0x3e0293ee, v111
	v_exp_f32_e32 v104, v10
	v_fmamk_f32 v10, v11, 0x3e0293ee, v111
	v_exp_f32_e32 v106, v8
	v_fmamk_f32 v8, v9, 0x3e0293ee, v111
	v_exp_f32_e32 v108, v6
	v_fmamk_f32 v6, v7, 0x3e0293ee, v111
	v_exp_f32_e32 v110, v4
	v_fmac_f32_e32 v111, 0x3e0293ee, v5
	v_pk_add_f32 v[4:5], v[92:93], 0 op_sel_hi:[1,0]
	v_exp_f32_e32 v14, v14
	v_exp_f32_e32 v15, v15
	v_pk_add_f32 v[4:5], v[82:83], v[4:5]
	v_exp_f32_e32 v103, v99
	v_pk_add_f32 v[4:5], v[94:95], v[4:5]
	v_exp_f32_e32 v101, v12
	v_pk_add_f32 v[4:5], v[16:17], v[4:5]
	v_exp_f32_e32 v98, v98
	v_exp_f32_e32 v99, v90
	v_pk_add_f32 v[4:5], v[96:97], v[4:5]
	v_exp_f32_e32 v105, v10
	v_pk_add_f32 v[4:5], v[14:15], v[4:5]
	v_exp_f32_e32 v88, v88
	v_exp_f32_e32 v89, v89
	v_pk_add_f32 v[4:5], v[102:103], v[4:5]
	v_exp_f32_e32 v107, v8
	v_pk_add_f32 v[4:5], v[100:101], v[4:5]
	v_exp_f32_e32 v86, v86
	v_exp_f32_e32 v87, v87
	v_pk_add_f32 v[4:5], v[98:99], v[4:5]
	v_exp_f32_e32 v109, v6
	v_pk_add_f32 v[4:5], v[104:105], v[4:5]
	v_exp_f32_e32 v84, v84
	v_exp_f32_e32 v85, v85
	v_pk_add_f32 v[4:5], v[88:89], v[4:5]
	v_exp_f32_e32 v111, v111
	v_pk_add_f32 v[4:5], v[106:107], v[4:5]
	v_cvt_pk_f16_f32 v6, v96, v97
	v_pk_add_f32 v[4:5], v[86:87], v[4:5]
	v_cvt_pk_f16_f32 v7, v102, v103
	v_pk_add_f32 v[4:5], v[108:109], v[4:5]
	v_cvt_pk_f16_f32 v8, v98, v99
	v_pk_add_f32 v[4:5], v[84:85], v[4:5]
	v_cvt_pk_f16_f32 v9, v88, v89
	v_pk_add_f32 v[4:5], v[110:111], v[4:5]
	v_cvt_pk_f16_f32 v10, v86, v87
	v_pk_add_f32 v[4:5], v[4:5], v[4:5] op_sel:[0,1] op_sel_hi:[1,0]
	v_cvt_pk_f16_f32 v11, v84, v85
	v_mov_b32_e32 v5, v4
	s_nop 1
	v_permlane32_swap_b32_e32 v4, v5
	v_add_f32_e32 v196, v4, v5
	v_cvt_pk_f16_f32 v4, v92, v93
	v_cvt_pk_f16_f32 v5, v94, v95
	v_cvt_pk_f16_f32 v12, v82, v83
	v_cvt_pk_f16_f32 v13, v16, v17
	v_cvt_pk_f16_f32 v14, v14, v15
	v_cvt_pk_f16_f32 v15, v100, v101
	v_cvt_pk_f16_f32 v82, v104, v105
	v_cvt_pk_f16_f32 v83, v106, v107
	v_cvt_pk_f16_f32 v84, v108, v109
	v_cvt_pk_f16_f32 v85, v110, v111
	v_fmac_f32_e32 v196, v190, v91
	v_permlane32_swap_b32_e32 v4, v6
	v_permlane32_swap_b32_e32 v5, v7
	v_permlane32_swap_b32_e32 v8, v10
	v_permlane32_swap_b32_e32 v9, v11
	v_permlane32_swap_b32_e32 v12, v14
	v_permlane32_swap_b32_e32 v13, v15
	v_permlane32_swap_b32_e32 v82, v84
	v_permlane32_swap_b32_e32 v83, v85
	v_add_u32_e32 v2, v187, v2
	ds_read_b64_tr_b16 v[86:87], v2 offset:0
	ds_read_b64_tr_b16 v[88:89], v2 offset:0x800
	ds_read_b64_tr_b16 v[90:91], v2 offset:0x1000
	ds_read_b64_tr_b16 v[92:93], v2 offset:0x1800
	ds_read_b64_tr_b16 v[94:95], v2 offset:0x2000
	ds_read_b64_tr_b16 v[96:97], v2 offset:0x2800
	ds_read_b64_tr_b16 v[98:99], v2 offset:0x3000
	ds_read_b64_tr_b16 v[100:101], v2 offset:0x3800
	ds_read_b64_tr_b16 v[102:103], v2 offset:0x200
	ds_read_b64_tr_b16 v[104:105], v2 offset:0xa00
	ds_read_b64_tr_b16 v[106:107], v2 offset:0x1200
	ds_read_b64_tr_b16 v[108:109], v2 offset:0x1a00
	ds_read_b64_tr_b16 v[110:111], v2 offset:0x2200
	ds_read_b64_tr_b16 v[112:113], v2 offset:0x2a00
	ds_read_b64_tr_b16 v[190:191], v2 offset:0x3200
	ds_read_b64_tr_b16 v[192:193], v2 offset:0x3a00
	s_waitcnt lgkmcnt(8)
	s_nop 0
	v_mfma_f32_32x32x16_f16 v[66:81], v[4:7], v[86:89], v[66:81]
	v_mfma_f32_32x32x16_f16 v[66:81], v[8:11], v[90:93], v[66:81]
	v_mfma_f32_32x32x16_f16 v[66:81], v[12:15], v[94:97], v[66:81]
	v_mfma_f32_32x32x16_f16 v[66:81], v[82:85], v[98:101], v[66:81]
	ds_read_b64_tr_b16 v[86:87], v2 offset:0x400
	ds_read_b64_tr_b16 v[88:89], v2 offset:0xc00
	ds_read_b64_tr_b16 v[90:91], v2 offset:0x1400
	ds_read_b64_tr_b16 v[92:93], v2 offset:0x1c00
	ds_read_b64_tr_b16 v[94:95], v2 offset:0x2400
	ds_read_b64_tr_b16 v[96:97], v2 offset:0x2c00
	ds_read_b64_tr_b16 v[98:99], v2 offset:0x3400
	ds_read_b64_tr_b16 v[100:101], v2 offset:0x3c00
	s_waitcnt lgkmcnt(8)
	v_mfma_f32_32x32x16_f16 v[50:65], v[4:7], v[102:105], v[50:65]
	v_mfma_f32_32x32x16_f16 v[50:65], v[8:11], v[106:109], v[50:65]
	v_mfma_f32_32x32x16_f16 v[50:65], v[12:15], v[110:113], v[50:65]
	v_mfma_f32_32x32x16_f16 v[50:65], v[82:85], v[190:193], v[50:65]
	ds_read_b64_tr_b16 v[102:103], v2 offset:0x600
	ds_read_b64_tr_b16 v[104:105], v2 offset:0xe00
	ds_read_b64_tr_b16 v[106:107], v2 offset:0x1600
	ds_read_b64_tr_b16 v[108:109], v2 offset:0x1e00
	ds_read_b64_tr_b16 v[110:111], v2 offset:0x2600
	ds_read_b64_tr_b16 v[112:113], v2 offset:0x2e00
	ds_read_b64_tr_b16 v[192:193], v2 offset:0x3600
	ds_read_b64_tr_b16 v[194:195], v2 offset:0x3e00
	s_waitcnt lgkmcnt(8)
	v_mfma_f32_32x32x16_f16 v[34:49], v[4:7], v[86:89], v[34:49]
	v_mfma_f32_32x32x16_f16 v[34:49], v[8:11], v[90:93], v[34:49]
	v_mfma_f32_32x32x16_f16 v[34:49], v[12:15], v[94:97], v[34:49]
	v_mfma_f32_32x32x16_f16 v[34:49], v[82:85], v[98:101], v[34:49]
	s_waitcnt lgkmcnt(0)
	v_mfma_f32_32x32x16_f16 v[18:33], v[4:7], v[102:105], v[18:33]
	v_mov_b32_e32 v190, v196
	v_mfma_f32_32x32x16_f16 v[18:33], v[8:11], v[106:109], v[18:33]
	v_mfma_f32_32x32x16_f16 v[18:33], v[12:15], v[110:113], v[18:33]
	v_mfma_f32_32x32x16_f16 v[18:33], v[82:85], v[192:195], v[18:33]
; #define FA_SBAR() __builtin_amdgcn_sched_barrier(0)
; #define FA_WRITET(bf) do { *(LAS half8*)(lds + OFF_K + (bf) * SHM_K + kws) = st_k0; *(LAS half8*)(lds + OFF_K + (bf) * SHM_K + kws + 32 * 256) = st_k1; \
;         *(LAS half8*)(lds + OFF_V + (bf) * SHM_V + vst0) = st_v0; *(LAS half8*)(lds + OFF_V + (bf) * SHM_V + vst1) = st_v1; \
;         if constexpr (MLA) *(LAS half8*)(lds + OFF_KR + (bf) * SHM_KR + krw) = st_kr; } while (0)
; template <int KIND>
; __device__ __forceinline__ void run_unit(LAS char* lds, const UnitArgs& U, int tid_in) {
;     ...
;     for (int t = 0; t < NT; ++t) {
;         if (t + 1 < NT) FA_LOADT(U.j_lo + t + 1);
;         FA_SBAR();
;         FA_STEP(t);
;         FA_SBAR();
;         if (t + 1 < NT) { asm volatile("s_waitcnt vmcnt(0)" ::: "memory"); FA_WRITET((t + 1) & 1); dm_lo = dn_lo; dm_hi = dn_hi; }
;         __syncthreads();
.LBB0_5000:
	s_branch .LBB0_4989
.Lslc_skipq:
	s_and_b64 vcc, exec, s[6:7]
	s_cbranch_vccz .LBB0_5000
	v_readfirstlane_b32 vcc_hi, v0
	s_and_b32 vcc_lo, s37, 0x4000
	s_lshr_b32 vcc_hi, vcc_hi, 6
	s_lshl_b32 vcc_hi, vcc_hi, 10
	s_add_i32 vcc_lo, vcc_lo, vcc_hi
	v_add_u32_e32 v2, s22, v166
	v_add_u32_e32 v4, 1, v2
	v_ashrrev_i32_e32 v5, 31, v4
	v_add_u32_e32 v8, 33, v2
	v_lshlrev_b64 v[4:5], 8, v[4:5]
	v_ashrrev_i32_e32 v9, 31, v8
	s_add_i32 m0, vcc_lo, 0x8000
	v_lshl_add_u64 v[6:7], v[170:171], 0, v[4:5]
	v_lshlrev_b64 v[8:9], 8, v[8:9]
	global_load_lds_dwordx4 v[6:7], off
	s_add_i32 m0, vcc_lo, 0xa000
	v_lshl_add_u64 v[10:11], v[170:171], 0, v[8:9]
	v_lshl_add_u64 v[4:5], v[172:173], 0, v[4:5]
	global_load_lds_dwordx4 v[10:11], off
	s_mov_b32 m0, vcc_lo
	v_lshl_add_u64 v[6:7], v[172:173], 0, v[8:9]
	s_nop 0
	global_load_lds_dwordx4 v[4:5], off
	s_add_i32 m0, vcc_lo, 0x2000
	s_nop 0
	global_load_lds_dwordx4 v[6:7], off
	s_branch .LBB0_5000
